# L2 warm-up extended: last MLA unit's tail touches the first NA unit's K/V rows
# speedup vs baseline: 1.0081x; 1.0081x over previous
.LBB0_1380:
	s_add_i32 s98, s37, 1
	s_lshl_b32 s98, s98, 3
	s_or_b32 s98, s98, s3
	s_mul_i32 s98, s98, s21
	s_add_i32 s98, s98, s20
	s_cmpk_gt_i32 s98, 0x3ff
	s_cbranch_scc1 .Lmla_warmna
	s_bfe_u32 s99, s98, 0x30003
	s_mul_i32 s99, s99, 0xc0
	s_ashr_i32 s100, s98, 6
	s_lshl_b32 s100, s100, 11
	s_lshl_b32 s98, s98, 8
	s_and_b32 s98, s98, 0x700
	s_or_b32 s98, s100, s98
	v_lshrrev_b32_e32 v236, 1, v162
	v_add_u32_e32 v236, s98, v236
	v_and_b32_e32 v238, 1, v162
	v_lshlrev_b32_e32 v238, 7, v238
	v_add_u32_e32 v238, s99, v238
	v_mov_b32_e32 v239, 0
	v_mad_i64_i32 v[236:237], s[100:101], v236, s29, v[238:239]
	v_lshl_add_u64 v[236:237], s[18:19], 0, v[236:237]
	global_load_dword v240, v[236:237], off
	s_branch .Lmla_nowarm
.Lmla_warmna:
	s_min_i32 s98, s28, 0x7ff
	s_bfe_u32 s99, s98, 0x30004
	s_lshl_b32 s99, s99, 7
	s_and_b32 s100, s98, 15
	s_lshl_b32 s100, s100, 1
	s_sub_i32 s100, s100, 4
	s_max_i32 s100, s100, 0
	s_min_i32 s100, s100, 24
	s_lshl_b32 s100, s100, 6
	s_ashr_i32 s101, s98, 7
	s_lshl_b32 s98, s101, 11
	s_add_i32 s100, s100, s98
	s_lshl_b32 s101, s101, 8
	s_add_i32 s101, s101, 0x8000
	v_cmp_gt_u32_e32 vcc, 0x100, v162
	v_mov_b32_e32 v238, 0x4400000
	v_mov_b32_e32 v239, 0x2000000
	s_nop 0
	v_cndmask_b32_e32 v238, v239, v238, vcc
	v_add_u32_e32 v238, s99, v238
	v_and_b32_e32 v236, 0xff, v162
	v_and_b32_e32 v237, 63, v162
	v_add_u32_e32 v240, s101, v236
	v_lshl_add_u32 v240, v240, 10, v238
	v_mov_b32_e32 v241, 0
	v_add_u32_e32 v242, s100, v236
	v_lshl_add_u32 v242, v242, 10, v238
	v_mov_b32_e32 v243, 0
	v_add_u32_e32 v244, 0x40000, v242
	v_mov_b32_e32 v245, 0
	v_add_u32_e32 v237, s100, v237
	v_add_u32_e32 v237, 0x200, v237
	v_lshl_add_u32 v236, v237, 10, v238
	v_mov_b32_e32 v237, 0
	v_lshl_add_u64 v[240:241], s[64:65], 0, v[240:241]
	v_lshl_add_u64 v[242:243], s[64:65], 0, v[242:243]
	v_lshl_add_u64 v[244:245], s[64:65], 0, v[244:245]
	v_lshl_add_u64 v[236:237], s[64:65], 0, v[236:237]
	global_load_dword v240, v[240:241], off
	global_load_dword v242, v[242:243], off
	global_load_dword v244, v[244:245], off
	global_load_dword v236, v[236:237], off
